# v32 plus 368 unreachable s_nop after the window code so that all later code keeps the byte offsets it had before the window rewrite (placement control)
# baseline (speedup 1.0000x reference)
; __device__ __forceinline__ void partialSM(f32x16& p0, f32x16& p1, float& m_reg, float& mn, float& alpha) {
;     float pmax = p0[0];
; #pragma unroll
;     for (int r = 1; r < 16; ++r) pmax = fmaxf(pmax, p0[r]);
; #pragma unroll
;     for (int r = 0; r < 16; ++r) pmax = fmaxf(pmax, p1[r]);
;     { auto rr = __builtin_amdgcn_permlane32_swap(__float_as_uint(pmax), __float_as_uint(pmax), false, false);
;       pmax = fmaxf(__uint_as_float(rr[0]), __uint_as_float(rr[1])); }
;     constexpr float C2 = 1.4426950408889634f * SM_SCALE;
;     if (__builtin_expect(__all((pmax - m_reg) * SM_SCALE <= THR), 1)) { mn = m_reg; alpha = 1.f; }
;     else { mn = fmaxf(m_reg, pmax); alpha = __builtin_amdgcn_exp2f((m_reg - mn) * C2); m_reg = mn; }
;     const float mnL = -mn * C2;
; #pragma unroll
;     for (int r = 0; r < 16; ++r) p0[r] = fmaf(p0[r], C2, mnL);
; #pragma unroll
;     for (int r = 0; r < 16; ++r) p1[r] = fmaf(p1[r], C2, mnL);
; #pragma unroll
;     for (int r = 0; r < 16; ++r) p0[r] = __builtin_amdgcn_exp2f(p0[r]);
; }
; __device__ __forceinline__ void finishSM(f32x16& p0, f32x16& p1, float alpha, float& l_reg, bf16x8& pa0, bf16x8& pa1, bf16x8& pa2, bf16x8& pa3) {
; #pragma unroll
;     for (int r = 0; r < 16; ++r) p1[r] = __builtin_amdgcn_exp2f(p1[r]);
;     float ps = 0;
; #pragma unroll
;     for (int r = 0; r < 16; ++r) ps += p0[r];
; #pragma unroll
;     for (int r = 0; r < 16; ++r) ps += p1[r];
;     { auto rr = __builtin_amdgcn_permlane32_swap(__float_as_uint(ps), __float_as_uint(ps), false, false);
;       ps = __uint_as_float(rr[0]) + __uint_as_float(rr[1]); }
;     l_reg = l_reg * alpha + ps;
;     PK4(p0, 0, pa0); PK4(p0, 8, pa1); PK4(p1, 0, pa2); PK4(p1, 8, pa3);
; }
; template <int MODE, bool DV2>
; __device__ __forceinline__ void attn_block2(const BlockRef& cur, char* lds, const int wid) {
;     ...
;     if (t < NT) {
;         STEP2(pB0, pB1, mnB, alB, actB, pA0, pA1, alA, actA, t);
;         if (!SK || actB) finishSM(pB0, pB1, alB, l_reg, pa0, pa1, pa2, pa3); SBAR();
;         pv_tile<0, SK>(o, vbase + ((NT - 1) % 3) * VST, pa0, pa1, pa2, pa3, actB);
;         if (DV2) pv_tile<0, SK>(o2, vbase + ((NT - 1) % 3) * VST + SHM_V, pa0, pa1, pa2, pa3, actB);
;     } else {
;         if (!SK || actA) finishSM(pA0, pA1, alA, l_reg, pa0, pa1, pa2, pa3); SBAR();
;         pv_tile<0, SK>(o, vbase + ((NT - 1) % 3) * VST, pa0, pa1, pa2, pa3, actA);
.LBB0_945:
	v_cndmask_b32_e64 v65, v65, v185, s[2:3]
	v_mul_f32_e32 v65, 0xbe0293ee, v65
	v_fmamk_f32 v66, v96, 0x3e0293ee, v65
	v_fmamk_f32 v67, v97, 0x3e0293ee, v65
	v_exp_f32_e32 v66, v66
	v_fmamk_f32 v68, v98, 0x3e0293ee, v65
	v_exp_f32_e32 v67, v67
	v_fmamk_f32 v69, v99, 0x3e0293ee, v65
	v_exp_f32_e32 v68, v68
	v_fmamk_f32 v70, v100, 0x3e0293ee, v65
	v_fmamk_f32 v71, v101, 0x3e0293ee, v65
	v_fmamk_f32 v72, v102, 0x3e0293ee, v65
	v_fmamk_f32 v73, v103, 0x3e0293ee, v65
	v_fmamk_f32 v74, v104, 0x3e0293ee, v65
	v_fmamk_f32 v75, v105, 0x3e0293ee, v65
	v_fmamk_f32 v76, v106, 0x3e0293ee, v65
	v_fmamk_f32 v77, v107, 0x3e0293ee, v65
	v_fmamk_f32 v78, v108, 0x3e0293ee, v65
	v_fmamk_f32 v79, v109, 0x3e0293ee, v65
	v_fmamk_f32 v80, v110, 0x3e0293ee, v65
	v_fmamk_f32 v81, v111, 0x3e0293ee, v65
	v_fmamk_f32 v82, v112, 0x3e0293ee, v65
	v_fmamk_f32 v83, v113, 0x3e0293ee, v65
	v_fmamk_f32 v84, v114, 0x3e0293ee, v65
	v_fmamk_f32 v85, v115, 0x3e0293ee, v65
	v_fmamk_f32 v86, v116, 0x3e0293ee, v65
	v_fmamk_f32 v87, v117, 0x3e0293ee, v65
	v_fmamk_f32 v88, v118, 0x3e0293ee, v65
	v_fmamk_f32 v89, v119, 0x3e0293ee, v65
	v_fmamk_f32 v90, v120, 0x3e0293ee, v65
	v_fmamk_f32 v91, v121, 0x3e0293ee, v65
	v_fmamk_f32 v92, v122, 0x3e0293ee, v65
	v_fmamk_f32 v93, v123, 0x3e0293ee, v65
	v_fmamk_f32 v94, v124, 0x3e0293ee, v65
	v_fmamk_f32 v95, v125, 0x3e0293ee, v65
	v_fmamk_f32 v96, v126, 0x3e0293ee, v65
	v_fmac_f32_e32 v65, 0x3e0293ee, v127
	v_exp_f32_e32 v69, v69
	v_exp_f32_e32 v70, v70
	v_exp_f32_e32 v98, v65
	v_add_f32_e32 v65, 0, v66
	v_exp_f32_e32 v71, v71
	v_add_f32_e32 v65, v67, v65
	v_exp_f32_e32 v72, v72
	v_add_f32_e32 v65, v68, v65
	v_exp_f32_e32 v73, v73
	v_add_f32_e32 v65, v69, v65
	v_exp_f32_e32 v74, v74
	v_add_f32_e32 v65, v70, v65
	v_exp_f32_e32 v75, v75
	v_add_f32_e32 v65, v71, v65
	v_exp_f32_e32 v76, v76
	v_add_f32_e32 v65, v72, v65
	v_exp_f32_e32 v77, v77
	v_add_f32_e32 v65, v73, v65
	v_exp_f32_e32 v78, v78
	v_add_f32_e32 v65, v74, v65
	v_exp_f32_e32 v79, v79
	v_add_f32_e32 v65, v75, v65
	v_exp_f32_e32 v80, v80
	v_add_f32_e32 v65, v76, v65
	v_exp_f32_e32 v81, v81
	v_add_f32_e32 v65, v77, v65
	v_exp_f32_e32 v82, v82
	v_add_f32_e32 v65, v78, v65
	v_exp_f32_e32 v83, v83
	v_add_f32_e32 v65, v79, v65
	v_exp_f32_e32 v84, v84
	v_add_f32_e32 v65, v80, v65
	v_exp_f32_e32 v85, v85
	v_add_f32_e32 v65, v81, v65
	v_exp_f32_e32 v86, v86
	v_add_f32_e32 v65, v82, v65
	v_exp_f32_e32 v87, v87
	v_add_f32_e32 v65, v83, v65
	v_exp_f32_e32 v88, v88
	v_add_f32_e32 v65, v84, v65
	v_exp_f32_e32 v89, v89
	v_add_f32_e32 v65, v85, v65
	v_exp_f32_e32 v90, v90
	v_add_f32_e32 v65, v86, v65
	v_exp_f32_e32 v91, v91
	v_add_f32_e32 v65, v87, v65
	v_exp_f32_e32 v92, v92
	v_add_f32_e32 v65, v88, v65
	v_exp_f32_e32 v93, v93
	v_add_f32_e32 v65, v89, v65
	v_exp_f32_e32 v94, v94
	v_add_f32_e32 v65, v90, v65
	v_exp_f32_e32 v95, v95
	v_add_f32_e32 v65, v91, v65
	v_exp_f32_e32 v96, v96
	v_add_f32_e32 v65, v92, v65
	v_add_f32_e32 v65, v93, v65
	v_add_f32_e32 v65, v94, v65
	v_add_f32_e32 v65, v95, v65
	v_add_f32_e32 v65, v96, v65
	v_add_f32_e32 v65, v98, v65
	v_mov_b32_e32 v99, v65
	v_add_f32_e32 v97, v128, v129
	s_nop 0
	v_permlane32_swap_b32_e32 v65, v99
	v_fmac_f32_e32 v97, v176, v189
	s_waitcnt vmcnt(0) lgkmcnt(0)
	s_barrier
	v_add_f32_e32 v210, v65, v99
	v_fmac_f32_e32 v210, v97, v64
	v_cvt_pk_bf16_f32 v64, v66, v67
	v_cvt_pk_bf16_f32 v65, v68, v69
	v_cvt_pk_bf16_f32 v66, v70, v71
	v_cvt_pk_bf16_f32 v67, v72, v73
	v_cvt_pk_bf16_f32 v68, v74, v75
	v_cvt_pk_bf16_f32 v69, v76, v77
	v_cvt_pk_bf16_f32 v70, v78, v79
	v_cvt_pk_bf16_f32 v71, v80, v81
	v_cvt_pk_bf16_f32 v72, v82, v83
	v_cvt_pk_bf16_f32 v73, v84, v85
	v_cvt_pk_bf16_f32 v74, v86, v87
	v_cvt_pk_bf16_f32 v75, v88, v89
	v_cvt_pk_bf16_f32 v76, v90, v91
	v_cvt_pk_bf16_f32 v77, v92, v93
	v_cvt_pk_bf16_f32 v78, v94, v95
	v_cvt_pk_bf16_f32 v79, v96, v98
	s_nop 0
	v_permlane32_swap_b32_e32 v64, v66
	v_permlane32_swap_b32_e32 v65, v67
	v_permlane32_swap_b32_e32 v68, v70
	v_permlane32_swap_b32_e32 v69, v71
	v_permlane32_swap_b32_e32 v72, v74
	v_permlane32_swap_b32_e32 v73, v75
	v_permlane32_swap_b32_e32 v76, v78
	v_permlane32_swap_b32_e32 v77, v79
	s_add_i32 s26, s26, -1
	s_mul_hi_i32 s0, s26, 0x55555556
	s_lshr_b32 s1, s0, 31
	s_add_i32 s0, s0, s1
	s_mul_i32 s0, s0, 3
	s_sub_i32 s0, s26, s0
	v_lshl_add_u32 v96, s0, 14, v175
	ds_read_b64_tr_b16 v[80:81], v96 offset:0
	ds_read_b64_tr_b16 v[82:83], v96 offset:0x800
	ds_read_b64_tr_b16 v[84:85], v96 offset:0x1000
	ds_read_b64_tr_b16 v[86:87], v96 offset:0x1800
	ds_read_b64_tr_b16 v[88:89], v96 offset:0x2000
	ds_read_b64_tr_b16 v[90:91], v96 offset:0x2800
	ds_read_b64_tr_b16 v[92:93], v96 offset:0x3000
	ds_read_b64_tr_b16 v[94:95], v96 offset:0x3800
	s_waitcnt lgkmcnt(0)
	s_nop 0
	v_mfma_f32_32x32x16_bf16 v[16:31], v[64:67], v[80:83], v[16:31]
	ds_read_b64_tr_b16 v[80:81], v96 offset:0x200
	ds_read_b64_tr_b16 v[82:83], v96 offset:0xa00
	v_mfma_f32_32x32x16_bf16 v[16:31], v[68:71], v[84:87], v[16:31]
	ds_read_b64_tr_b16 v[84:85], v96 offset:0x1200
	ds_read_b64_tr_b16 v[86:87], v96 offset:0x1a00
	v_mfma_f32_32x32x16_bf16 v[16:31], v[72:75], v[88:91], v[16:31]
	ds_read_b64_tr_b16 v[88:89], v96 offset:0x2200
	ds_read_b64_tr_b16 v[90:91], v96 offset:0x2a00
	v_mfma_f32_32x32x16_bf16 v[16:31], v[76:79], v[92:95], v[16:31]
	ds_read_b64_tr_b16 v[92:93], v96 offset:0x3200
	ds_read_b64_tr_b16 v[94:95], v96 offset:0x3a00
	s_waitcnt lgkmcnt(0)
; template <int MODE, bool DV2>
; __device__ __forceinline__ void attn_block2(const BlockRef& cur, char* lds, const int wid) {
;     ...
;         pv_tile<0, SK>(o, vbase + ((NT - 1) % 3) * VST, pa0, pa1, pa2, pa3, actA);
;         if (DV2) pv_tile<0, SK>(o2, vbase + ((NT - 1) % 3) * VST + SHM_V, pa0, pa1, pa2, pa3, actA);
;     }
;     if (hi == 0) li_l[r32] = l_reg; asm volatile("s_waitcnt lgkmcnt(0)" ::: "memory");
	v_mfma_f32_32x32x16_bf16 v[32:47], v[64:67], v[80:83], v[32:47]
	ds_read_b64_tr_b16 v[80:81], v96 offset:0x400
	ds_read_b64_tr_b16 v[82:83], v96 offset:0xc00
	v_mfma_f32_32x32x16_bf16 v[32:47], v[68:71], v[84:87], v[32:47]
	ds_read_b64_tr_b16 v[84:85], v96 offset:0x1400
	ds_read_b64_tr_b16 v[86:87], v96 offset:0x1c00
	v_mfma_f32_32x32x16_bf16 v[32:47], v[72:75], v[88:91], v[32:47]
	ds_read_b64_tr_b16 v[88:89], v96 offset:0x2400
	ds_read_b64_tr_b16 v[90:91], v96 offset:0x2c00
	v_mfma_f32_32x32x16_bf16 v[32:47], v[76:79], v[92:95], v[32:47]
	ds_read_b64_tr_b16 v[92:93], v96 offset:0x3400
	ds_read_b64_tr_b16 v[94:95], v96 offset:0x3c00
	s_waitcnt lgkmcnt(0)
	v_mfma_f32_32x32x16_bf16 v[48:63], v[64:67], v[80:83], v[48:63]
	ds_read_b64_tr_b16 v[80:81], v96 offset:0x600
	ds_read_b64_tr_b16 v[82:83], v96 offset:0xe00
	v_mfma_f32_32x32x16_bf16 v[48:63], v[68:71], v[84:87], v[48:63]
	ds_read_b64_tr_b16 v[84:85], v96 offset:0x1600
	ds_read_b64_tr_b16 v[86:87], v96 offset:0x1e00
	v_mfma_f32_32x32x16_bf16 v[48:63], v[72:75], v[88:91], v[48:63]
	ds_read_b64_tr_b16 v[88:89], v96 offset:0x2600
	ds_read_b64_tr_b16 v[90:91], v96 offset:0x2e00
	v_mfma_f32_32x32x16_bf16 v[48:63], v[76:79], v[92:95], v[48:63]
	ds_read_b64_tr_b16 v[92:93], v96 offset:0x3600
	ds_read_b64_tr_b16 v[94:95], v96 offset:0x3e00
	s_waitcnt lgkmcnt(0)
	v_mfma_f32_32x32x16_bf16 v[0:15], v[64:67], v[80:83], v[0:15]
	s_nop 10
	v_mov_b64_e32 v[110:111], v[62:63]
	v_mov_b64_e32 v[108:109], v[60:61]
	v_mov_b64_e32 v[106:107], v[58:59]
	v_mov_b64_e32 v[104:105], v[56:57]
	v_mov_b64_e32 v[102:103], v[54:55]
	v_mov_b64_e32 v[100:101], v[52:53]
	v_mov_b64_e32 v[98:99], v[50:51]
	v_mfma_f32_32x32x16_bf16 v[0:15], v[68:71], v[84:87], v[0:15]
	v_mov_b64_e32 v[96:97], v[48:49]
	v_mfma_f32_32x32x16_bf16 v[0:15], v[72:75], v[88:91], v[0:15]
	v_mfma_f32_32x32x16_bf16 v[0:15], v[76:79], v[92:95], v[0:15]
	v_mov_b64_e32 v[94:95], v[46:47]
	v_mov_b64_e32 v[78:79], v[30:31]
	v_mov_b64_e32 v[92:93], v[44:45]
	v_mov_b64_e32 v[90:91], v[42:43]
	v_mov_b64_e32 v[88:89], v[40:41]
	v_mov_b64_e32 v[86:87], v[38:39]
	v_mov_b64_e32 v[84:85], v[36:37]
	s_nop 4
	v_mov_b64_e32 v[126:127], v[14:15]
	v_mov_b64_e32 v[82:83], v[34:35]
	v_mov_b64_e32 v[80:81], v[32:33]
	v_mov_b64_e32 v[124:125], v[12:13]
	v_mov_b64_e32 v[122:123], v[10:11]
	v_mov_b64_e32 v[120:121], v[8:9]
	v_mov_b64_e32 v[118:119], v[6:7]
	v_mov_b64_e32 v[116:117], v[4:5]
	v_mov_b64_e32 v[114:115], v[2:3]
	v_mov_b64_e32 v[112:113], v[0:1]
	v_mov_b64_e32 v[76:77], v[28:29]
	v_mov_b64_e32 v[74:75], v[26:27]
	v_mov_b64_e32 v[72:73], v[24:25]
	v_mov_b64_e32 v[70:71], v[22:23]
	v_mov_b64_e32 v[68:69], v[20:21]
	v_mov_b64_e32 v[66:67], v[18:19]
	v_mov_b64_e32 v[64:65], v[16:17]
	v_cmp_gt_u32_e32 vcc, 32, v170
	s_and_saveexec_b64 s[2:3], vcc
	s_cbranch_execnz .LBB0_773
	s_branch .LBB0_774
	s_nop 0
	s_nop 0
	s_nop 0
	s_nop 0
	s_nop 0
	s_nop 0
	s_nop 0
	s_nop 0
	s_nop 0
	s_nop 0
	s_nop 0
	s_nop 0
	s_nop 0
	s_nop 0
	s_nop 0
	s_nop 0
	s_nop 0
	s_nop 0
	s_nop 0
	s_nop 0
	s_nop 0
	s_nop 0
	s_nop 0
	s_nop 0
	s_nop 0
	s_nop 0
	s_nop 0
	s_nop 0
	s_nop 0
	s_nop 0
	s_nop 0
	s_nop 0
	s_nop 0
	s_nop 0
	s_nop 0
	s_nop 0
	s_nop 0
	s_nop 0
	s_nop 0
	s_nop 0
	s_nop 0
	s_nop 0
	s_nop 0
	s_nop 0
	s_nop 0
	s_nop 0
	s_nop 0
	s_nop 0
	s_nop 0
	s_nop 0
	s_nop 0
	s_nop 0
	s_nop 0
	s_nop 0
	s_nop 0
	s_nop 0
	s_nop 0
	s_nop 0
	s_nop 0
	s_nop 0
	s_nop 0
	s_nop 0
	s_nop 0
	s_nop 0
	s_nop 0
	s_nop 0
	s_nop 0
	s_nop 0
	s_nop 0
	s_nop 0
	s_nop 0
	s_nop 0
	s_nop 0
	s_nop 0
	s_nop 0
	s_nop 0
	s_nop 0
	s_nop 0
	s_nop 0
	s_nop 0
	s_nop 0
	s_nop 0
	s_nop 0
	s_nop 0
	s_nop 0
	s_nop 0
	s_nop 0
	s_nop 0
	s_nop 0
	s_nop 0
	s_nop 0
	s_nop 0
	s_nop 0
	s_nop 0
	s_nop 0
	s_nop 0
	s_nop 0
	s_nop 0
	s_nop 0
	s_nop 0
	s_nop 0
	s_nop 0
	s_nop 0
	s_nop 0
	s_nop 0
	s_nop 0
	s_nop 0
	s_nop 0
	s_nop 0
	s_nop 0
	s_nop 0
	s_nop 0
	s_nop 0
	s_nop 0
	s_nop 0
	s_nop 0
	s_nop 0
	s_nop 0
	s_nop 0
	s_nop 0
	s_nop 0
	s_nop 0
	s_nop 0
	s_nop 0
	s_nop 0
	s_nop 0
	s_nop 0
	s_nop 0
	s_nop 0
	s_nop 0
	s_nop 0
	s_nop 0
	s_nop 0
	s_nop 0
	s_nop 0
	s_nop 0
	s_nop 0
	s_nop 0
	s_nop 0
	s_nop 0
	s_nop 0
	s_nop 0
	s_nop 0
	s_nop 0
	s_nop 0
	s_nop 0
	s_nop 0
	s_nop 0
	s_nop 0
	s_nop 0
	s_nop 0
	s_nop 0
	s_nop 0
	s_nop 0
	s_nop 0
	s_nop 0
	s_nop 0
	s_nop 0
	s_nop 0
	s_nop 0
	s_nop 0
	s_nop 0
	s_nop 0
	s_nop 0
	s_nop 0
	s_nop 0
	s_nop 0
	s_nop 0
	s_nop 0
	s_nop 0
	s_nop 0
	s_nop 0
	s_nop 0
	s_nop 0
	s_nop 0
	s_nop 0
	s_nop 0
	s_nop 0
	s_nop 0
	s_nop 0
	s_nop 0
	s_nop 0
	s_nop 0
	s_nop 0
	s_nop 0
	s_nop 0
	s_nop 0
	s_nop 0
	s_nop 0
	s_nop 0
	s_nop 0
	s_nop 0
	s_nop 0
	s_nop 0
	s_nop 0
	s_nop 0
	s_nop 0
	s_nop 0
	s_nop 0
	s_nop 0
	s_nop 0
	s_nop 0
	s_nop 0
	s_nop 0
	s_nop 0
	s_nop 0
	s_nop 0
	s_nop 0
	s_nop 0
	s_nop 0
	s_nop 0
	s_nop 0
	s_nop 0
	s_nop 0
	s_nop 0
	s_nop 0
	s_nop 0
	s_nop 0
	s_nop 0
	s_nop 0
	s_nop 0
	s_nop 0
	s_nop 0
	s_nop 0
	s_nop 0
	s_nop 0
	s_nop 0
	s_nop 0
	s_nop 0
	s_nop 0
	s_nop 0
	s_nop 0
	s_nop 0
	s_nop 0
	s_nop 0
	s_nop 0
	s_nop 0
	s_nop 0
	s_nop 0
	s_nop 0
	s_nop 0
	s_nop 0
	s_nop 0
	s_nop 0
	s_nop 0
	s_nop 0
	s_nop 0
	s_nop 0
	s_nop 0
	s_nop 0
	s_nop 0
	s_nop 0
	s_nop 0
	s_nop 0
	s_nop 0
	s_nop 0
	s_nop 0
	s_nop 0
	s_nop 0
	s_nop 0
	s_nop 0
	s_nop 0
	s_nop 0
	s_nop 0
	s_nop 0
	s_nop 0
	s_nop 0
	s_nop 0
	s_nop 0
	s_nop 0
	s_nop 0
	s_nop 0
	s_nop 0
	s_nop 0
	s_nop 0
	s_nop 0
	s_nop 0
	s_nop 0
	s_nop 0
	s_nop 0
	s_nop 0
	s_nop 0
	s_nop 0
	s_nop 0
	s_nop 0
	s_nop 0
	s_nop 0
	s_nop 0
	s_nop 0
	s_nop 0
	s_nop 0
	s_nop 0
	s_nop 0
	s_nop 0
	s_nop 0
	s_nop 0
	s_nop 0
	s_nop 0
	s_nop 0
	s_nop 0
	s_nop 0
	s_nop 0
	s_nop 0
	s_nop 0
	s_nop 0
	s_nop 0
	s_nop 0
	s_nop 0
	s_nop 0
	s_nop 0
	s_nop 0
	s_nop 0
	s_nop 0
	s_nop 0
	s_nop 0
	s_nop 0
	s_nop 0
	s_nop 0
	s_nop 0
	s_nop 0
	s_nop 0
	s_nop 0
	s_nop 0
	s_nop 0
	s_nop 0
	s_nop 0
	s_nop 0
	s_nop 0
	s_nop 0
	s_nop 0
	s_nop 0
	s_nop 0
	s_nop 0
	s_nop 0
	s_nop 0
	s_nop 0
	s_nop 0
	s_nop 0
	s_nop 0
	s_nop 0
	s_nop 0
	s_nop 0
	s_nop 0
	s_nop 0
	s_nop 0
	s_nop 0
	s_nop 0
	s_nop 0
	s_nop 0
	s_nop 0
	s_nop 0
	s_nop 0
	s_nop 0
	s_nop 0
	s_nop 0
	s_nop 0
	s_nop 0
	s_nop 0
	s_nop 0
	s_nop 0
	s_nop 0
	s_nop 0
	s_nop 0
	s_nop 0
	s_nop 0
	s_nop 0
	s_nop 0
	s_nop 0
